# conversion item: pointer table via scalar loads, 4 tiles of loads in flight, single wait before stores
# speedup vs baseline: 1.0098x; 1.0098x over previous
.LBB0_415:
	s_cmpk_gt_u32 s30, 0xff
	s_cbranch_scc0 .LBB0_421
	s_cmpk_gt_u32 s30, 0x1ff
	s_cbranch_scc0 .LBB0_422
	s_cmpk_gt_u32 s30, 0x2ff
	s_cbranch_scc0 .LBB0_423
	s_cmpk_gt_u32 s30, 0x85f
	s_mul_i32 s12, s31, 0x2b00000
	s_cbranch_scc0 .LBB0_600
	s_mov_b64 s[8:9], s[4:5]
	s_load_dwordx2 s[100:101], s[4:5], 0x98
	s_add_i32 s42, s30, 0xfffff7a0
	s_mul_i32 s8, s31, 0x1580000
	v_readlane_b32 s9, v254, 23
	s_mov_b32 s13, s15
	s_add_u32 s8, s9, s8
	v_readlane_b32 s9, v254, 24
	s_addc_u32 s9, s9, 0
	s_waitcnt lgkmcnt(0)
	v_mov_b32_e32 v130, s100
	v_mov_b32_e32 v131, s101
	v_lshl_add_u64 v[130:131], v[130:131], 0, s[12:13]
	s_cbranch_execz .LBB0_601
	s_mov_b64 s[26:27], 0x1580
	s_mov_b64 s[38:39], 0x800
	s_movk_i32 s43, 0x1580
	s_cbranch_execz .LBB0_424
	s_branch .LBB0_425

.LBB0_423:
.LBB0_424:
	s_mov_b64 s[8:9], s[4:5]
	s_load_dwordx2 s[100:101], s[4:5], 0x68
	s_add_i32 s42, s30, 0xfffffe00
	s_lshl_b32 s14, s31, 24
	s_lshl_b32 s8, s31, 23
	v_readlane_b32 s9, v254, 27
	s_add_u32 s8, s9, s8
	v_readlane_b32 s9, v254, 28
	s_mov_b64 s[38:39], 0x800
	s_movk_i32 s43, 0x800
	s_addc_u32 s9, s9, 0
	s_mov_b64 s[26:27], 0x800
	s_waitcnt lgkmcnt(0)
	v_mov_b32_e32 v130, s100
	v_mov_b32_e32 v131, s101
	v_lshl_add_u64 v[130:131], v[130:131], 0, s[14:15]

.LBB0_426:
	s_mov_b64 s[8:9], s[4:5]
	s_load_dwordx2 s[100:101], s[4:5], 0x60
	s_add_i32 s42, s30, 0xffffff00
	s_lshl_b32 s14, s31, 24
	s_add_u32 s8, s54, s14
	s_addc_u32 s9, s55, 0
	s_add_u32 s8, s8, 0x81a1200
	s_addc_u32 s9, s9, 0
	s_mov_b64 s[26:27], 0x1000
	s_mov_b64 s[38:39], 0x800
	s_movk_i32 s43, 0x800
	s_waitcnt lgkmcnt(0)
	v_mov_b32_e32 v130, s100
	v_mov_b32_e32 v131, s101
	v_lshl_add_u64 v[130:131], v[130:131], 0, s[14:15]

.LBB0_428:
	s_mov_b64 s[8:9], s[4:5]
	s_load_dwordx2 s[100:101], s[4:5], 0x58
	s_lshl_b32 s14, s31, 24
	v_readlane_b32 s8, v254, 29
	s_add_u32 s8, s8, s14
	v_readlane_b32 s9, v254, 30
	s_mov_b64 s[26:27], 0x1000
	s_mov_b64 s[38:39], 0x800
	s_movk_i32 s43, 0x800
	s_addc_u32 s9, s9, 0
	s_mov_b32 s42, s30
	s_waitcnt lgkmcnt(0)
	v_mov_b32_e32 v130, s100
	v_mov_b32_e32 v131, s101
	v_lshl_add_u64 v[130:131], v[130:131], 0, s[14:15]
.LBB0_429:
	s_mov_b64 s[12:13], 0
	s_andn2_b64 vcc, exec, s[0:1]
	s_mov_b64 s[64:65], 0
	s_cbranch_vccnz .LBB0_431
	s_mov_b64 s[0:1], s[4:5]
	s_load_dwordx2 s[100:101], s[4:5], 0x20
	s_mov_b64 s[0:1], 0x8000000
	v_readlane_b32 s8, v254, 31
	s_add_i32 s42, s78, 0xfffff4e0
	s_mov_b64 s[64:65], -1
	s_movk_i32 s43, 0x800
	s_mov_b64 s[38:39], 0x4000
	s_mov_b64 s[26:27], 0x800
	v_readlane_b32 s9, v254, 32
	s_waitcnt lgkmcnt(0)
	v_mov_b32_e32 v130, s100
	v_mov_b32_e32 v131, s101
	v_lshl_add_u64 v[130:131], v[130:131], 0, s[0:1]

.LBB0_436:
	s_cmpk_lt_u32 s22, 0x100
	s_cbranch_scc1 .LBB0_442
	s_cmpk_lt_u32 s22, 0x200
	s_cbranch_scc1 .LBB0_443
	s_cmpk_lt_u32 s22, 0x300
	s_cbranch_scc1 .LBB0_444
	s_cmpk_lt_u32 s22, 0x860
	s_mul_i32 s14, s23, 0x2b00000
	s_cbranch_scc1 .LBB0_602
	s_mov_b64 s[6:7], s[4:5]
	s_load_dwordx2 s[100:101], s[4:5], 0x98
	s_add_i32 s79, s22, 0xfffff7a0
	s_mul_i32 s6, s23, 0x1580000
	v_readlane_b32 s7, v254, 23
	s_add_u32 s48, s7, s6
	v_readlane_b32 s6, v254, 24
	s_addc_u32 s49, s6, 0
	s_waitcnt lgkmcnt(0)
	v_mov_b32_e32 v132, s100
	v_mov_b32_e32 v133, s101
	v_lshl_add_u64 v[132:133], v[132:133], 0, s[14:15]
	s_cbranch_execz .LBB0_603
	s_mov_b64 s[50:51], 0x1580
	s_mov_b64 s[44:45], 0x800
	s_movk_i32 s80, 0x1580
	s_cbranch_execz .LBB0_445
	s_branch .LBB0_446

.LBB0_444:
.LBB0_445:
	s_mov_b64 s[6:7], s[4:5]
	s_nop 0
	s_load_dwordx2 s[100:101], s[4:5], 0x68
	s_add_i32 s79, s22, 0xfffffe00
	s_lshl_b32 s14, s23, 24
	s_lshl_b32 s6, s23, 23
	v_readlane_b32 s7, v254, 27
	s_add_u32 s48, s7, s6
	v_readlane_b32 s6, v254, 28
	s_mov_b64 s[44:45], 0x800
	s_movk_i32 s80, 0x800
	s_addc_u32 s49, s6, 0
	s_mov_b64 s[50:51], 0x800
	s_waitcnt lgkmcnt(0)
	v_mov_b32_e32 v132, s100
	v_mov_b32_e32 v133, s101
	v_lshl_add_u64 v[132:133], v[132:133], 0, s[14:15]

.LBB0_447:
	s_mov_b64 s[6:7], s[4:5]
	s_load_dwordx2 s[100:101], s[4:5], 0x60
	s_add_i32 s79, s22, 0xffffff00
	s_lshl_b32 s14, s23, 24
	s_add_u32 s6, s54, s14
	s_addc_u32 s7, s55, 0
	s_add_u32 s48, s6, 0x81a1200
	s_addc_u32 s49, s7, 0
	s_mov_b64 s[50:51], 0x1000
	s_mov_b64 s[44:45], 0x800
	s_movk_i32 s80, 0x800
	s_waitcnt lgkmcnt(0)
	v_mov_b32_e32 v132, s100
	v_mov_b32_e32 v133, s101
	v_lshl_add_u64 v[132:133], v[132:133], 0, s[14:15]

.LBB0_449:
	s_mov_b64 s[6:7], s[4:5]
	s_load_dwordx2 s[100:101], s[4:5], 0x58
	s_lshl_b32 s14, s23, 24
	v_readlane_b32 s6, v254, 29
	s_add_u32 s48, s6, s14
	v_readlane_b32 s6, v254, 30
	s_mov_b64 s[50:51], 0x1000
	s_mov_b64 s[44:45], 0x800
	s_movk_i32 s80, 0x800
	s_addc_u32 s49, s6, 0
	s_mov_b32 s79, s22
	s_waitcnt lgkmcnt(0)
	v_mov_b32_e32 v132, s100
	v_mov_b32_e32 v133, s101
	v_lshl_add_u64 v[132:133], v[132:133], 0, s[14:15]
.LBB0_450:
	s_mov_b64 s[6:7], 0
	s_andn2_b64 vcc, exec, s[12:13]
	s_mov_b64 s[12:13], 0
	s_cbranch_vccnz .LBB0_452
	s_mov_b64 s[12:13], s[4:5]
	s_load_dwordx2 s[100:101], s[4:5], 0x20
	s_mov_b64 s[22:23], 0x8000000
	v_readlane_b32 s48, v254, 31
	s_add_i32 s79, s78, 0xfffff4e1
	s_mov_b64 s[12:13], -1
	s_movk_i32 s80, 0x800
	s_mov_b64 s[44:45], 0x4000
	s_mov_b64 s[50:51], 0x800
	v_readlane_b32 s49, v254, 32
	s_waitcnt lgkmcnt(0)
	v_mov_b32_e32 v132, s100
	v_mov_b32_e32 v133, s101
	v_lshl_add_u64 v[132:133], v[132:133], 0, s[22:23]

.LBB0_457:
	s_cmpk_lt_u32 s30, 0x100
	s_cbranch_scc1 .LBB0_463
	s_cmpk_lt_u32 s30, 0x200
	s_cbranch_scc1 .LBB0_464
	s_cmpk_lt_u32 s30, 0x300
	s_cbranch_scc1 .LBB0_465
	s_cmpk_lt_u32 s30, 0x860
	s_mul_i32 s14, s31, 0x2b00000
	s_cbranch_scc1 .LBB0_604
	s_mov_b64 s[22:23], s[4:5]
	s_load_dwordx2 s[100:101], s[4:5], 0x98
	s_add_i32 s81, s30, 0xfffff7a0
	s_mul_i32 s22, s31, 0x1580000
	v_readlane_b32 s23, v254, 23
	s_add_u32 s52, s23, s22
	v_readlane_b32 s22, v254, 24
	s_addc_u32 s53, s22, 0
	s_waitcnt lgkmcnt(0)
	v_mov_b32_e32 v134, s100
	v_mov_b32_e32 v135, s101
	v_lshl_add_u64 v[134:135], v[134:135], 0, s[14:15]
	s_cbranch_execz .LBB0_605
	s_mov_b64 s[40:41], 0x1580
	s_mov_b64 s[66:67], 0x800
	s_movk_i32 s82, 0x1580
	s_cbranch_execz .LBB0_466
	s_branch .LBB0_467

.LBB0_465:
.LBB0_466:
	s_mov_b64 s[22:23], s[4:5]
	s_load_dwordx2 s[100:101], s[4:5], 0x68
	s_add_i32 s81, s30, 0xfffffe00
	s_lshl_b32 s14, s31, 24
	s_lshl_b32 s22, s31, 23
	v_readlane_b32 s23, v254, 27
	s_add_u32 s52, s23, s22
	v_readlane_b32 s22, v254, 28
	s_mov_b64 s[66:67], 0x800
	s_movk_i32 s82, 0x800
	s_addc_u32 s53, s22, 0
	s_mov_b64 s[40:41], 0x800
	s_waitcnt lgkmcnt(0)
	v_mov_b32_e32 v134, s100
	v_mov_b32_e32 v135, s101
	v_lshl_add_u64 v[134:135], v[134:135], 0, s[14:15]

.LBB0_468:
	s_mov_b64 s[22:23], s[4:5]
	s_load_dwordx2 s[100:101], s[4:5], 0x60
	s_add_i32 s81, s30, 0xffffff00
	s_lshl_b32 s14, s31, 24
	s_mov_b64 s[40:41], 0x1000
	s_mov_b64 s[66:67], 0x800
	s_movk_i32 s82, 0x800
	s_waitcnt lgkmcnt(0)
	v_mov_b32_e32 v134, s100
	v_mov_b32_e32 v135, s101
	v_lshl_add_u64 v[134:135], v[134:135], 0, s[14:15]
	s_add_u32 s14, s54, s14
	s_addc_u32 s22, s55, 0
	s_add_u32 s52, s14, 0x81a1200
	s_addc_u32 s53, s22, 0

.LBB0_470:
	s_mov_b64 s[22:23], s[4:5]
	s_load_dwordx2 s[100:101], s[4:5], 0x58
	s_lshl_b32 s14, s31, 24
	v_readlane_b32 s22, v254, 29
	s_add_u32 s52, s22, s14
	v_readlane_b32 s22, v254, 30
	s_mov_b64 s[40:41], 0x1000
	s_mov_b64 s[66:67], 0x800
	s_movk_i32 s82, 0x800
	s_addc_u32 s53, s22, 0
	s_mov_b32 s81, s30
	s_waitcnt lgkmcnt(0)
	v_mov_b32_e32 v134, s100
	v_mov_b32_e32 v135, s101
	v_lshl_add_u64 v[134:135], v[134:135], 0, s[14:15]
.LBB0_471:
	s_mov_b64 s[30:31], 0
	s_andn2_b64 vcc, exec, s[6:7]
	s_mov_b64 s[22:23], 0
	s_cbranch_vccnz .LBB0_473
	s_mov_b64 s[6:7], s[4:5]
	s_load_dwordx2 s[100:101], s[4:5], 0x20
	s_mov_b64 s[6:7], 0x8000000
	v_readlane_b32 s52, v254, 31
	s_add_i32 s81, s78, 0xfffff4e2
	s_mov_b64 s[22:23], -1
	s_movk_i32 s82, 0x800
	s_mov_b64 s[66:67], 0x4000
	s_mov_b64 s[40:41], 0x800
	v_readlane_b32 s53, v254, 32
	s_waitcnt lgkmcnt(0)
	v_mov_b32_e32 v134, s100
	v_mov_b32_e32 v135, s101
	v_lshl_add_u64 v[134:135], v[134:135], 0, s[6:7]

.LBB0_478:
	s_cmpk_lt_u32 s83, 0x100
	s_cbranch_scc1 .LBB0_484
	s_cmpk_lt_u32 s83, 0x200
	s_cbranch_scc1 .LBB0_485
	s_cmpk_lt_u32 s83, 0x300
	s_cbranch_scc1 .LBB0_486
	s_cmpk_lt_u32 s83, 0x860
	s_mul_i32 s14, s84, 0x2b00000
	s_cbranch_scc1 .LBB0_606
	s_mov_b64 s[0:1], s[4:5]
	s_load_dwordx2 s[100:101], s[4:5], 0x98
	s_add_i32 s86, s83, 0xfffff7a0
	s_mul_i32 s0, s84, 0x1580000
	v_readlane_b32 s1, v254, 23
	s_add_u32 s6, s1, s0
	v_readlane_b32 s0, v254, 24
	s_addc_u32 s7, s0, 0
	s_waitcnt lgkmcnt(0)
	v_mov_b32_e32 v136, s100
	v_mov_b32_e32 v137, s101
	v_lshl_add_u64 v[138:139], v[136:137], 0, s[14:15]
	s_cbranch_execz .LBB0_607
	s_mov_b64 s[60:61], 0x1580
	s_mov_b64 s[68:69], 0x800
	s_movk_i32 s89, 0x1580
	s_cbranch_execz .LBB0_487
	s_branch .LBB0_488

.LBB0_486:
.LBB0_487:
	s_mov_b64 s[0:1], s[4:5]
	s_nop 0
	s_load_dwordx2 s[100:101], s[4:5], 0x68
	s_add_i32 s86, s83, 0xfffffe00
	s_lshl_b32 s14, s84, 24
	s_lshl_b32 s0, s84, 23
	v_readlane_b32 s1, v254, 27
	s_add_u32 s6, s1, s0
	v_readlane_b32 s0, v254, 28
	s_mov_b64 s[68:69], 0x800
	s_movk_i32 s89, 0x800
	s_addc_u32 s7, s0, 0
	s_mov_b64 s[60:61], 0x800
	s_waitcnt lgkmcnt(0)
	v_mov_b32_e32 v136, s100
	v_mov_b32_e32 v137, s101
	v_lshl_add_u64 v[138:139], v[136:137], 0, s[14:15]

.LBB0_489:
	s_mov_b64 s[0:1], s[4:5]
	s_load_dwordx2 s[100:101], s[4:5], 0x60
	s_add_i32 s86, s83, 0xffffff00
	s_lshl_b32 s14, s84, 24
	s_add_u32 s0, s54, s14
	s_addc_u32 s1, s55, 0
	s_add_u32 s6, s0, 0x81a1200
	s_addc_u32 s7, s1, 0
	s_mov_b64 s[60:61], 0x1000
	s_mov_b64 s[68:69], 0x800
	s_movk_i32 s89, 0x800
	s_waitcnt lgkmcnt(0)
	v_mov_b32_e32 v136, s100
	v_mov_b32_e32 v137, s101
	v_lshl_add_u64 v[138:139], v[136:137], 0, s[14:15]

.LBB0_491:
	s_mov_b64 s[0:1], s[4:5]
	s_load_dwordx2 s[100:101], s[4:5], 0x58
	s_lshl_b32 s14, s84, 24
	v_readlane_b32 s0, v254, 29
	s_add_u32 s6, s0, s14
	v_readlane_b32 s0, v254, 30
	s_mov_b64 s[60:61], 0x1000
	s_mov_b64 s[68:69], 0x800
	s_movk_i32 s89, 0x800
	s_addc_u32 s7, s0, 0
	s_mov_b32 s86, s83
	s_waitcnt lgkmcnt(0)
	v_mov_b32_e32 v136, s100
	v_mov_b32_e32 v137, s101
	v_lshl_add_u64 v[138:139], v[136:137], 0, s[14:15]
.LBB0_492:
	s_andn2_b64 vcc, exec, s[30:31]
	s_mov_b64 s[30:31], 0
	s_cbranch_vccnz .LBB0_494
	s_mov_b64 s[0:1], s[4:5]
	s_load_dwordx2 s[100:101], s[4:5], 0x20
	s_mov_b64 s[0:1], 0x8000000
	v_readlane_b32 s6, v254, 31
	s_add_i32 s86, s78, 0xfffff4e3
	s_mov_b64 s[30:31], -1
	s_movk_i32 s89, 0x800
	s_mov_b64 s[68:69], 0x4000
	s_mov_b64 s[60:61], 0x800
	v_readlane_b32 s7, v254, 32
	s_waitcnt lgkmcnt(0)
	v_mov_b32_e32 v136, s100
	v_mov_b32_e32 v137, s101
	v_lshl_add_u64 v[138:139], v[136:137], 0, s[0:1]
.LBB0_494:
	s_add_i32 s0, s43, 0xff
	s_lshr_b32 s14, s0, 8
	v_cvt_f32_u32_e32 v136, s14
	s_and_b32 s0, s42, 0xffff
	v_cvt_f32_u32_e32 v0, s0
	v_rcp_iflag_f32_e32 v137, v136
	s_nop 0
	v_mul_f32_e32 v137, v0, v137
	v_trunc_f32_e32 v137, v137
	v_fma_f32 v0, -v137, v136, v0
	v_cvt_u32_f32_e32 v137, v137
	v_cmp_ge_f32_e64 s[0:1], |v0|, v136
	s_cmp_lg_u64 s[0:1], 0
	v_readfirstlane_b32 s83, v137
	s_addc_u32 s0, s83, 0
	s_and_b32 s88, s0, 0xffff
	s_mul_i32 s0, s0, s14
	s_sub_i32 s0, s42, s0
	s_lshl_b32 s0, s0, 8
	s_and_b32 s0, s0, 0xff00
	s_lshl_b32 s87, s88, 6
	v_add_u32_e32 v140, s0, v143
	v_or_b32_e32 v152, s87, v142
	v_cmp_gt_i32_e32 vcc, s43, v140
	v_ashrrev_i32_e32 v141, 31, v140
	s_and_saveexec_b64 s[0:1], vcc
	s_cbranch_execz .LBB0_496
	v_or_b32_e32 v66, 2, v140
	v_or_b32_e32 v98, 4, v140
	v_or_b32_e32 v122, 6, v140
	v_mul_lo_u32 v126, s38, v141
	v_mul_lo_u32 v68, s39, v66
	v_mad_u64_u32 v[66:67], s[42:43], s38, v66, 0
	v_mul_lo_u32 v100, s39, v98
	v_mad_u64_u32 v[98:99], s[42:43], s38, v98, 0
	v_mul_lo_u32 v124, s39, v122
	v_mad_u64_u32 v[122:123], s[42:43], s38, v122, 0
	v_or_b32_e32 v36, 1, v140
	v_add3_u32 v67, v67, v126, v68
	v_or_b32_e32 v68, 3, v140
	v_add3_u32 v99, v99, v126, v100
	v_or_b32_e32 v100, 5, v140
	v_add3_u32 v123, v123, v126, v124
	v_or_b32_e32 v124, 7, v140
	v_mul_lo_u32 v0, s39, v140
	v_mad_u64_u32 v[34:35], s[42:43], s38, v140, 0
	v_mul_lo_u32 v38, s39, v36
	v_mad_u64_u32 v[36:37], s[42:43], s38, v36, 0
	v_mul_lo_u32 v70, s39, v68
	v_mad_u64_u32 v[68:69], s[42:43], s38, v68, 0
	v_mul_lo_u32 v102, s39, v100
	v_mad_u64_u32 v[100:101], s[42:43], s38, v100, 0
	v_mul_lo_u32 v127, s39, v124
	v_mad_u64_u32 v[124:125], s[38:39], s38, v124, 0
	v_add3_u32 v35, v35, v126, v0
	v_add3_u32 v37, v37, v126, v38
	v_add3_u32 v69, v69, v126, v70
	v_add3_u32 v101, v101, v126, v102
	v_add3_u32 v125, v125, v126, v127
	v_lshl_add_u64 v[34:35], v[34:35], 2, v[130:131]
	v_lshlrev_b32_e32 v0, 2, v152
	v_lshl_add_u64 v[36:37], v[36:37], 2, v[130:131]
	v_lshl_add_u64 v[66:67], v[66:67], 2, v[130:131]
	v_lshl_add_u64 v[68:69], v[68:69], 2, v[130:131]
	v_lshl_add_u64 v[98:99], v[98:99], 2, v[130:131]
	v_lshl_add_u64 v[100:101], v[100:101], 2, v[130:131]
	v_lshl_add_u64 v[122:123], v[122:123], 2, v[130:131]
	v_lshl_add_u64 v[124:125], v[124:125], 2, v[130:131]
	v_lshl_add_u64 v[34:35], v[34:35], 0, v[0:1]
	v_lshl_add_u64 v[36:37], v[36:37], 0, v[0:1]
	v_lshl_add_u64 v[66:67], v[66:67], 0, v[0:1]
	v_lshl_add_u64 v[68:69], v[68:69], 0, v[0:1]
	v_lshl_add_u64 v[98:99], v[98:99], 0, v[0:1]
	v_lshl_add_u64 v[100:101], v[100:101], 0, v[0:1]
	v_lshl_add_u64 v[122:123], v[122:123], 0, v[0:1]
	v_lshl_add_u64 v[124:125], v[124:125], 0, v[0:1]
	global_load_dwordx4 v[38:41], v[34:35], off nt
	s_nop 0
	global_load_dwordx4 v[34:37], v[36:37], off nt
	s_nop 0
	global_load_dwordx4 v[70:73], v[66:67], off nt
	s_nop 0
	global_load_dwordx4 v[66:69], v[68:69], off nt
	s_nop 0
	global_load_dwordx4 v[102:105], v[98:99], off nt
	s_nop 0
	global_load_dwordx4 v[98:101], v[100:101], off nt
	s_nop 0
	global_load_dwordx4 v[126:129], v[122:123], off nt
	s_nop 0
	global_load_dwordx4 v[122:125], v[124:125], off nt
.LBB0_496:
	s_or_b64 exec, exec, s[0:1]
	s_add_i32 s0, s80, 0xff
	s_lshr_b32 s14, s0, 8
	v_cvt_f32_u32_e32 v130, s14
	s_and_b32 s0, s79, 0xffff
	v_cvt_f32_u32_e32 v0, s0
	v_rcp_iflag_f32_e32 v131, v130
	s_nop 0
	v_mul_f32_e32 v131, v0, v131
	v_trunc_f32_e32 v131, v131
	v_fma_f32 v0, -v131, v130, v0
	v_cvt_u32_f32_e32 v131, v131
	v_cmp_ge_f32_e64 s[0:1], |v0|, v130
	s_cmp_lg_u64 s[0:1], 0
	v_readfirstlane_b32 s38, v131
	s_addc_u32 s0, s38, 0
	s_and_b32 s85, s0, 0xffff
	s_mul_i32 s0, s0, s14
	s_sub_i32 s0, s79, s0
	s_lshl_b32 s0, s0, 8
	s_and_b32 s0, s0, 0xff00
	s_lshl_b32 s84, s85, 6
	v_add_u32_e32 v136, s0, v143
	v_or_b32_e32 v149, s84, v142
	v_cmp_gt_i32_e64 s[42:43], s80, v136
	v_ashrrev_i32_e32 v137, 31, v136
	s_and_saveexec_b64 s[0:1], s[42:43]
	s_cbranch_execz .LBB0_498
	v_or_b32_e32 v50, 2, v136
	v_or_b32_e32 v82, 4, v136
	v_or_b32_e32 v114, 6, v136
	v_mul_lo_u32 v118, s44, v137
	v_mul_lo_u32 v52, s45, v50
	v_mad_u64_u32 v[50:51], s[38:39], s44, v50, 0
	v_mul_lo_u32 v84, s45, v82
	v_mad_u64_u32 v[82:83], s[38:39], s44, v82, 0
	v_mul_lo_u32 v116, s45, v114
	v_mad_u64_u32 v[114:115], s[38:39], s44, v114, 0
	v_or_b32_e32 v20, 1, v136
	v_add3_u32 v51, v51, v118, v52
	v_or_b32_e32 v52, 3, v136
	v_add3_u32 v83, v83, v118, v84
	v_or_b32_e32 v84, 5, v136
	v_add3_u32 v115, v115, v118, v116
	v_or_b32_e32 v116, 7, v136
	v_mul_lo_u32 v0, s45, v136
	v_mad_u64_u32 v[18:19], s[38:39], s44, v136, 0
	v_mul_lo_u32 v22, s45, v20
	v_mad_u64_u32 v[20:21], s[38:39], s44, v20, 0
	v_mul_lo_u32 v54, s45, v52
	v_mad_u64_u32 v[52:53], s[38:39], s44, v52, 0
	v_mul_lo_u32 v86, s45, v84
	v_mad_u64_u32 v[84:85], s[38:39], s44, v84, 0
	v_mul_lo_u32 v119, s45, v116
	v_mad_u64_u32 v[116:117], s[38:39], s44, v116, 0
	v_add3_u32 v19, v19, v118, v0
	v_add3_u32 v21, v21, v118, v22
	v_add3_u32 v53, v53, v118, v54
	v_add3_u32 v85, v85, v118, v86
	v_add3_u32 v117, v117, v118, v119
	v_lshl_add_u64 v[18:19], v[18:19], 2, v[132:133]
	v_lshlrev_b32_e32 v0, 2, v149
	v_lshl_add_u64 v[20:21], v[20:21], 2, v[132:133]
	v_lshl_add_u64 v[50:51], v[50:51], 2, v[132:133]
	v_lshl_add_u64 v[52:53], v[52:53], 2, v[132:133]
	v_lshl_add_u64 v[82:83], v[82:83], 2, v[132:133]
	v_lshl_add_u64 v[84:85], v[84:85], 2, v[132:133]
	v_lshl_add_u64 v[114:115], v[114:115], 2, v[132:133]
	v_lshl_add_u64 v[116:117], v[116:117], 2, v[132:133]
	v_lshl_add_u64 v[18:19], v[18:19], 0, v[0:1]
	v_lshl_add_u64 v[20:21], v[20:21], 0, v[0:1]
	v_lshl_add_u64 v[50:51], v[50:51], 0, v[0:1]
	v_lshl_add_u64 v[52:53], v[52:53], 0, v[0:1]
	v_lshl_add_u64 v[82:83], v[82:83], 0, v[0:1]
	v_lshl_add_u64 v[84:85], v[84:85], 0, v[0:1]
	v_lshl_add_u64 v[114:115], v[114:115], 0, v[0:1]
	v_lshl_add_u64 v[116:117], v[116:117], 0, v[0:1]
	global_load_dwordx4 v[22:25], v[18:19], off nt
	s_nop 0
	global_load_dwordx4 v[18:21], v[20:21], off nt
	s_nop 0
	global_load_dwordx4 v[54:57], v[50:51], off nt
	s_nop 0
	global_load_dwordx4 v[50:53], v[52:53], off nt
	s_nop 0
	global_load_dwordx4 v[86:89], v[82:83], off nt
	s_nop 0
	global_load_dwordx4 v[82:85], v[84:85], off nt
	s_nop 0
	global_load_dwordx4 v[118:121], v[114:115], off nt
	s_nop 0
	global_load_dwordx4 v[114:117], v[116:117], off nt
.LBB0_498:
	s_or_b64 exec, exec, s[0:1]
	s_add_i32 s0, s82, 0xff
	s_lshr_b32 s14, s0, 8
	v_cvt_f32_u32_e32 v130, s14
	s_and_b32 s0, s81, 0xffff
	v_cvt_f32_u32_e32 v0, s0
	v_rcp_iflag_f32_e32 v131, v130
	s_nop 0
	v_mul_f32_e32 v131, v0, v131
	v_trunc_f32_e32 v131, v131
	v_fma_f32 v0, -v131, v130, v0
	v_cvt_u32_f32_e32 v131, v131
	v_cmp_ge_f32_e64 s[0:1], |v0|, v130
	s_cmp_lg_u64 s[0:1], 0
	v_readfirstlane_b32 s38, v131
	s_addc_u32 s0, s38, 0
	s_and_b32 s83, s0, 0xffff
	s_mul_i32 s0, s0, s14
	s_sub_i32 s0, s81, s0
	s_lshl_b32 s0, s0, 8
	s_and_b32 s0, s0, 0xff00
	s_lshl_b32 s80, s83, 6
	v_add_u32_e32 v132, s0, v143
	v_or_b32_e32 v147, s80, v142
	v_cmp_gt_i32_e64 s[38:39], s82, v132
	v_ashrrev_i32_e32 v133, 31, v132
	s_and_saveexec_b64 s[0:1], s[38:39]
	s_cbranch_execz .LBB0_500
	v_or_b32_e32 v42, 2, v132
	v_or_b32_e32 v74, 4, v132
	v_or_b32_e32 v106, 6, v132
	v_mul_lo_u32 v110, s66, v133
	v_mul_lo_u32 v44, s67, v42
	v_mad_u64_u32 v[42:43], s[44:45], s66, v42, 0
	v_mul_lo_u32 v76, s67, v74
	v_mad_u64_u32 v[74:75], s[44:45], s66, v74, 0
	v_mul_lo_u32 v108, s67, v106
	v_mad_u64_u32 v[106:107], s[44:45], s66, v106, 0
	v_or_b32_e32 v12, 1, v132
	v_add3_u32 v43, v43, v110, v44
	v_or_b32_e32 v44, 3, v132
	v_add3_u32 v75, v75, v110, v76
	v_or_b32_e32 v76, 5, v132
	v_add3_u32 v107, v107, v110, v108
	v_or_b32_e32 v108, 7, v132
	v_mul_lo_u32 v0, s67, v132
	v_mad_u64_u32 v[10:11], s[44:45], s66, v132, 0
	v_mul_lo_u32 v14, s67, v12
	v_mad_u64_u32 v[12:13], s[44:45], s66, v12, 0
	v_mul_lo_u32 v46, s67, v44
	v_mad_u64_u32 v[44:45], s[44:45], s66, v44, 0
	v_mul_lo_u32 v78, s67, v76
	v_mad_u64_u32 v[76:77], s[44:45], s66, v76, 0
	v_mul_lo_u32 v111, s67, v108
	v_mad_u64_u32 v[108:109], s[44:45], s66, v108, 0
	v_add3_u32 v11, v11, v110, v0
	v_add3_u32 v13, v13, v110, v14
	v_add3_u32 v45, v45, v110, v46
	v_add3_u32 v77, v77, v110, v78
	v_add3_u32 v109, v109, v110, v111
	v_lshl_add_u64 v[10:11], v[10:11], 2, v[134:135]
	v_lshlrev_b32_e32 v0, 2, v147
	v_lshl_add_u64 v[12:13], v[12:13], 2, v[134:135]
	v_lshl_add_u64 v[42:43], v[42:43], 2, v[134:135]
	v_lshl_add_u64 v[44:45], v[44:45], 2, v[134:135]
	v_lshl_add_u64 v[74:75], v[74:75], 2, v[134:135]
	v_lshl_add_u64 v[76:77], v[76:77], 2, v[134:135]
	v_lshl_add_u64 v[106:107], v[106:107], 2, v[134:135]
	v_lshl_add_u64 v[108:109], v[108:109], 2, v[134:135]
	v_lshl_add_u64 v[10:11], v[10:11], 0, v[0:1]
	v_lshl_add_u64 v[12:13], v[12:13], 0, v[0:1]
	v_lshl_add_u64 v[42:43], v[42:43], 0, v[0:1]
	v_lshl_add_u64 v[44:45], v[44:45], 0, v[0:1]
	v_lshl_add_u64 v[74:75], v[74:75], 0, v[0:1]
	v_lshl_add_u64 v[76:77], v[76:77], 0, v[0:1]
	v_lshl_add_u64 v[106:107], v[106:107], 0, v[0:1]
	v_lshl_add_u64 v[108:109], v[108:109], 0, v[0:1]
	global_load_dwordx4 v[14:17], v[10:11], off nt
	s_nop 0
	global_load_dwordx4 v[10:13], v[12:13], off nt
	s_nop 0
	global_load_dwordx4 v[46:49], v[42:43], off nt
	s_nop 0
	global_load_dwordx4 v[42:45], v[44:45], off nt
	s_nop 0
	global_load_dwordx4 v[78:81], v[74:75], off nt
	s_nop 0
	global_load_dwordx4 v[74:77], v[76:77], off nt
	s_nop 0
	global_load_dwordx4 v[110:113], v[106:107], off nt
	s_nop 0
	global_load_dwordx4 v[106:109], v[108:109], off nt
.LBB0_500:
	s_or_b64 exec, exec, s[0:1]
	s_add_i32 s0, s89, 0xff
	s_lshr_b32 s14, s0, 8
	v_cvt_f32_u32_e32 v130, s14
	s_and_b32 s0, s86, 0xffff
	v_cvt_f32_u32_e32 v0, s0
	v_rcp_iflag_f32_e32 v131, v130
	s_nop 0
	v_mul_f32_e32 v131, v0, v131
	v_trunc_f32_e32 v131, v131
	v_fma_f32 v0, -v131, v130, v0
	v_cvt_u32_f32_e32 v131, v131
	v_cmp_ge_f32_e64 s[0:1], |v0|, v130
	s_cmp_lg_u64 s[0:1], 0
	v_readfirstlane_b32 s44, v131
	s_addc_u32 s0, s44, 0
	s_and_b32 s79, s0, 0xffff
	s_mul_i32 s0, s0, s14
	s_sub_i32 s0, s86, s0
	s_lshl_b32 s0, s0, 8
	s_and_b32 s0, s0, 0xff00
	s_lshl_b32 s14, s79, 6
	v_add_u32_e32 v130, s0, v143
	v_or_b32_e32 v134, s14, v142
	v_cmp_gt_i32_e64 s[0:1], s89, v130
	v_ashrrev_i32_e32 v131, 31, v130
	s_and_saveexec_b64 s[44:45], s[0:1]
	s_cbranch_execz .LBB0_528
	v_or_b32_e32 v26, 2, v130
	v_or_b32_e32 v58, 4, v130
	v_or_b32_e32 v90, 6, v130
	v_mul_lo_u32 v94, s68, v131
	v_mul_lo_u32 v28, s69, v26
	v_mad_u64_u32 v[26:27], s[66:67], s68, v26, 0
	v_mul_lo_u32 v60, s69, v58
	v_mad_u64_u32 v[58:59], s[66:67], s68, v58, 0
	v_mul_lo_u32 v92, s69, v90
	v_mad_u64_u32 v[90:91], s[66:67], s68, v90, 0
	v_or_b32_e32 v4, 1, v130
	v_add3_u32 v27, v27, v94, v28
	v_or_b32_e32 v28, 3, v130
	v_add3_u32 v59, v59, v94, v60
	v_or_b32_e32 v60, 5, v130
	v_add3_u32 v91, v91, v94, v92
	v_or_b32_e32 v92, 7, v130
	v_mul_lo_u32 v0, s69, v130
	v_mad_u64_u32 v[2:3], s[66:67], s68, v130, 0
	v_mul_lo_u32 v6, s69, v4
	v_mad_u64_u32 v[4:5], s[66:67], s68, v4, 0
	v_mul_lo_u32 v30, s69, v28
	v_mad_u64_u32 v[28:29], s[66:67], s68, v28, 0
	v_mul_lo_u32 v62, s69, v60
	v_mad_u64_u32 v[60:61], s[66:67], s68, v60, 0
	v_mul_lo_u32 v95, s69, v92
	v_mad_u64_u32 v[92:93], s[66:67], s68, v92, 0
	v_add3_u32 v3, v3, v94, v0
	v_add3_u32 v5, v5, v94, v6
	v_add3_u32 v29, v29, v94, v30
	v_add3_u32 v61, v61, v94, v62
	v_add3_u32 v93, v93, v94, v95
	v_lshl_add_u64 v[2:3], v[2:3], 2, v[138:139]
	v_lshlrev_b32_e32 v0, 2, v134
	v_lshl_add_u64 v[4:5], v[4:5], 2, v[138:139]
	v_lshl_add_u64 v[26:27], v[26:27], 2, v[138:139]
	v_lshl_add_u64 v[28:29], v[28:29], 2, v[138:139]
	v_lshl_add_u64 v[58:59], v[58:59], 2, v[138:139]
	v_lshl_add_u64 v[60:61], v[60:61], 2, v[138:139]
	v_lshl_add_u64 v[90:91], v[90:91], 2, v[138:139]
	v_lshl_add_u64 v[92:93], v[92:93], 2, v[138:139]
	v_lshl_add_u64 v[2:3], v[2:3], 0, v[0:1]
	v_lshl_add_u64 v[4:5], v[4:5], 0, v[0:1]
	v_lshl_add_u64 v[26:27], v[26:27], 0, v[0:1]
	v_lshl_add_u64 v[28:29], v[28:29], 0, v[0:1]
	v_lshl_add_u64 v[58:59], v[58:59], 0, v[0:1]
	v_lshl_add_u64 v[60:61], v[60:61], 0, v[0:1]
	v_lshl_add_u64 v[90:91], v[90:91], 0, v[0:1]
	v_lshl_add_u64 v[92:93], v[92:93], 0, v[0:1]
	global_load_dwordx4 v[6:9], v[2:3], off nt
	s_nop 0
	global_load_dwordx4 v[2:5], v[4:5], off nt
	s_nop 0
	global_load_dwordx4 v[30:33], v[26:27], off nt
	s_nop 0
	global_load_dwordx4 v[26:29], v[28:29], off nt
	s_nop 0
	global_load_dwordx4 v[62:65], v[58:59], off nt
	s_nop 0
	global_load_dwordx4 v[58:61], v[60:61], off nt
	s_nop 0
	global_load_dwordx4 v[94:97], v[90:91], off nt
	s_nop 0
	global_load_dwordx4 v[90:93], v[92:93], off nt
	s_or_b64 exec, exec, s[44:45]
	s_waitcnt vmcnt(0)
	s_and_saveexec_b64 s[66:67], vcc
	s_cbranch_execnz .LBB0_529

.LBB0_508:
	v_mul_hi_i32_i24_e32 v153, s50, v0
	v_mul_i32_i24_e32 v152, s50, v0
	v_lshl_add_u64 v[152:153], v[152:153], 1, s[48:49]
	v_cvt_pk_bf16_f32 v138, v22, v18
	v_cvt_pk_bf16_f32 v139, v54, v50
	v_cvt_pk_bf16_f32 v140, v86, v82
	v_cvt_pk_bf16_f32 v141, v118, v114
	v_lshl_add_u64 v[152:153], v[136:137], 1, v[152:153]
	s_and_b64 vcc, exec, s[42:43]
	v_or_b32_e32 v0, 1, v149
	global_store_dwordx4 v[152:153], v[138:141], off
	s_cbranch_vccnz .LBB0_514
	s_movk_i32 s12, 0xffe
	v_cmp_lt_u32_e32 vcc, s12, v149
	v_lshlrev_b32_e32 v135, 1, v0
	s_and_saveexec_b64 s[12:13], vcc
	s_xor_b64 s[12:13], exec, s[12:13]
	s_and_b32 s26, s85, 0xffe0
	s_cmpk_eq_i32 s26, 0x60
	s_cselect_b64 vcc, -1, 0
	s_and_b32 s26, s84, 0x1f80
	s_and_b32 s27, s85, 1
	v_and_b32_e32 v135, 0x7a, v135
	s_or_b32 s26, s26, s27
	v_or_b32_e32 v135, s26, v135
	v_cndmask_b32_e32 v0, v0, v135, vcc
	s_andn2_saveexec_b64 s[12:13], s[12:13]
	v_and_b32_e32 v0, 58, v135
	v_or3_b32 v0, v145, v0, s84
	s_or_b64 exec, exec, s[12:13]

.LBB0_528:
	s_or_b64 exec, exec, s[44:45]
	s_waitcnt vmcnt(0)
	s_and_saveexec_b64 s[66:67], vcc
	s_cbranch_execz .LBB0_502

.LBB0_534:
	v_mul_hi_i32_i24_e32 v139, s26, v0
	v_mul_i32_i24_e32 v138, s26, v0
	v_lshl_add_u64 v[138:139], v[138:139], 1, s[8:9]
	v_cvt_pk_bf16_f32 v160, v38, v34
	v_cvt_pk_bf16_f32 v161, v70, v66
	v_cvt_pk_bf16_f32 v162, v102, v98
	v_cvt_pk_bf16_f32 v163, v126, v122
	v_lshl_add_u64 v[138:139], v[140:141], 1, v[138:139]
	s_and_b64 vcc, exec, s[44:45]
	v_or_b32_e32 v0, 1, v152
	global_store_dwordx4 v[138:139], v[160:163], off
	s_cbranch_vccnz .LBB0_540
	s_movk_i32 s64, 0xffe
	v_cmp_lt_u32_e32 vcc, s64, v152
	v_lshlrev_b32_e32 v135, 1, v0
	s_and_saveexec_b64 s[64:65], vcc
	s_xor_b64 s[64:65], exec, s[64:65]
	s_and_b32 s68, s88, 0x7fe0
	s_cmpk_eq_i32 s68, 0x60
	s_cselect_b64 vcc, -1, 0
	s_and_b32 s68, s87, 0x1f80
	s_and_b32 s69, s88, 1
	v_and_b32_e32 v135, 0x7a, v135
	s_or_b32 s68, s68, s69
	v_or_b32_e32 v135, s68, v135
	v_cndmask_b32_e32 v0, v0, v135, vcc
	s_andn2_saveexec_b64 s[64:65], s[64:65]
	v_and_b32_e32 v0, 58, v135
	v_or3_b32 v0, v145, v0, s87
	s_or_b64 exec, exec, s[64:65]

.LBB0_559:
	v_mul_hi_i32_i24_e32 v141, s40, v0
	v_mul_i32_i24_e32 v140, s40, v0
	v_lshl_add_u64 v[140:141], v[140:141], 1, s[52:53]
	v_cvt_pk_bf16_f32 v136, v14, v10
	v_cvt_pk_bf16_f32 v137, v46, v42
	v_cvt_pk_bf16_f32 v138, v78, v74
	v_cvt_pk_bf16_f32 v139, v110, v106
	v_lshl_add_u64 v[140:141], v[132:133], 1, v[140:141]
	s_and_b64 vcc, exec, s[38:39]
	v_or_b32_e32 v0, 1, v147
	global_store_dwordx4 v[140:141], v[136:139], off
	s_cbranch_vccnz .LBB0_565
	s_movk_i32 s12, 0xffe
	v_cmp_lt_u32_e32 vcc, s12, v147
	v_lshlrev_b32_e32 v135, 1, v0
	s_and_saveexec_b64 s[12:13], vcc
	s_xor_b64 s[12:13], exec, s[12:13]
	s_and_b32 s22, s83, 0x7fe0
	s_cmpk_eq_i32 s22, 0x60
	s_cselect_b64 vcc, -1, 0
	s_and_b32 s22, s80, 0x1f80
	s_and_b32 s23, s83, 1
	v_and_b32_e32 v135, 0x7a, v135
	s_or_b32 s22, s22, s23
	v_or_b32_e32 v135, s22, v135
	v_cndmask_b32_e32 v0, v0, v135, vcc
	s_andn2_saveexec_b64 s[12:13], s[12:13]
	v_and_b32_e32 v0, 58, v135
	v_or3_b32 v0, v145, v0, s80
	s_or_b64 exec, exec, s[12:13]

.LBB0_583:
	v_mul_hi_i32_i24_e32 v133, s60, v0
	v_mul_i32_i24_e32 v132, s60, v0
	v_lshl_add_u64 v[132:133], v[132:133], 1, s[6:7]
	v_cvt_pk_bf16_f32 v136, v6, v2
	v_cvt_pk_bf16_f32 v137, v30, v26
	v_cvt_pk_bf16_f32 v138, v62, v58
	v_cvt_pk_bf16_f32 v139, v94, v90
	v_lshl_add_u64 v[132:133], v[130:131], 1, v[132:133]
	s_and_b64 vcc, exec, s[0:1]
	v_or_b32_e32 v0, 1, v134
	global_store_dwordx4 v[132:133], v[136:139], off
	s_cbranch_vccnz .LBB0_589
	s_movk_i32 s12, 0xffe
	v_cmp_lt_u32_e32 vcc, s12, v134
	v_lshlrev_b32_e32 v132, 1, v0
	s_and_saveexec_b64 s[12:13], vcc
	s_xor_b64 s[12:13], exec, s[12:13]
	s_and_b32 s22, s79, 0x7fe0
	s_cmpk_eq_i32 s22, 0x60
	s_cselect_b64 vcc, -1, 0
	s_and_b32 s22, s14, 0x1f80
	s_and_b32 s23, s79, 1
	v_and_b32_e32 v132, 0x7a, v132
	s_or_b32 s22, s22, s23
	v_or_b32_e32 v132, s22, v132
	v_cndmask_b32_e32 v0, v0, v132, vcc
	s_andn2_saveexec_b64 s[12:13], s[12:13]
	v_and_b32_e32 v0, 58, v132
	v_or3_b32 v0, v145, v0, s14
	s_or_b64 exec, exec, s[12:13]

.LBB0_600:
.LBB0_601:
	s_mov_b64 s[8:9], s[4:5]
	s_load_dwordx2 s[100:101], s[4:5], 0x80
	s_add_i32 s42, s30, 0xfffffd00
	v_readlane_b32 s8, v254, 25
	s_mul_i32 s14, s31, 0x5600000
	s_add_u32 s8, s8, s12
	v_readlane_b32 s9, v254, 26
	s_addc_u32 s9, s9, 0
	s_mov_b64 s[26:27], 0x800
	s_mov_b64 s[38:39], 0x2b00
	s_movk_i32 s43, 0x800
	s_waitcnt lgkmcnt(0)
	v_mov_b32_e32 v130, s100
	v_mov_b32_e32 v131, s101
	v_lshl_add_u64 v[130:131], v[130:131], 0, s[14:15]
	s_cbranch_execz .LBB0_424
	s_branch .LBB0_425
.LBB0_602:
.LBB0_603:
	s_mov_b64 s[6:7], s[4:5]
	s_load_dwordx2 s[100:101], s[4:5], 0x80
	s_mul_i32 s6, s23, 0x5600000
	s_mov_b32 s7, s15
	s_add_i32 s79, s22, 0xfffffd00
	s_mov_b64 s[50:51], 0x800
	s_mov_b64 s[44:45], 0x2b00
	s_movk_i32 s80, 0x800
	s_waitcnt lgkmcnt(0)
	v_mov_b32_e32 v132, s100
	v_mov_b32_e32 v133, s101
	v_lshl_add_u64 v[132:133], v[132:133], 0, s[6:7]
	v_readlane_b32 s6, v254, 25
	s_add_u32 s48, s6, s14
	v_readlane_b32 s6, v254, 26
	s_addc_u32 s49, s6, 0
	s_cbranch_execz .LBB0_445
	s_branch .LBB0_446
.LBB0_604:
.LBB0_605:
	s_mov_b64 s[22:23], s[4:5]
	s_load_dwordx2 s[100:101], s[4:5], 0x80
	s_mul_i32 s22, s31, 0x5600000
	s_mov_b32 s23, s15
	s_add_i32 s81, s30, 0xfffffd00
	s_mov_b64 s[40:41], 0x800
	s_mov_b64 s[66:67], 0x2b00
	s_movk_i32 s82, 0x800
	s_waitcnt lgkmcnt(0)
	v_mov_b32_e32 v134, s100
	v_mov_b32_e32 v135, s101
	v_lshl_add_u64 v[134:135], v[134:135], 0, s[22:23]
	v_readlane_b32 s22, v254, 25
	s_add_u32 s52, s22, s14
	v_readlane_b32 s14, v254, 26
	s_addc_u32 s53, s14, 0
	s_cbranch_execz .LBB0_466
	s_branch .LBB0_467
.LBB0_606:
.LBB0_607:
	s_mov_b64 s[0:1], s[4:5]
	s_load_dwordx2 s[100:101], s[4:5], 0x80
	s_mul_i32 s0, s84, 0x5600000
	s_mov_b32 s1, s15
	s_add_i32 s86, s83, 0xfffffd00
	s_mov_b64 s[60:61], 0x800
	s_mov_b64 s[68:69], 0x2b00
	s_movk_i32 s89, 0x800
	s_waitcnt lgkmcnt(0)
	v_mov_b32_e32 v136, s100
	v_mov_b32_e32 v137, s101
	v_lshl_add_u64 v[138:139], v[136:137], 0, s[0:1]
	v_readlane_b32 s0, v254, 25
	s_add_u32 s6, s0, s14
	v_readlane_b32 s0, v254, 26
	s_addc_u32 s7, s0, 0
	s_cbranch_execz .LBB0_487
	s_branch .LBB0_488
